# v22_p3mid
# speedup vs baseline: 1.0073x; 1.0011x over previous
; __device__ __forceinline__ void gemm_prologue(const u16* __restrict__ A, const u16* __restrict__ Bt, const int K,
;                                               const int brow, const int bcol) {
;   int tid = threadIdx.x;
;   asm volatile("" : "+v"(tid));
;   const int tid16 = tid * 16;
;   int goff0, goff1;
;   { int R, C; stage_rc(tid16, R, C); goff0 = R * K + C; stage_rc(tid16 + 8192, R, C); goff1 = R * K + C; }
;   STAGE(SB(0, 0), Bt, bcol, 0); STAGE(SA(0, 0), A, brow, 0);
;   STAGE(SB(0, 1), Bt, bcol + HALF, 0); STAGE(SA(0, 1), A, brow + HALF, 0);
; }
; __device__ void phase3(const Params& p) {
;     ...
;     gemm_prologue(p.YB, p.WupbT, 2048, brow, bcol);
;     ...
;         for (int bj = 0; bj < 2; ++bj) {
;           asm volatile("" : "+v"(koff));
;           u32x4 sa[4], sb[4];
; #pragma unroll
;           for (int m = 0; m < 4; ++m) {
;             sa[m] = __builtin_nontemporal_load((const u32x4*)(gta + koff + ((ai * 2 + bj) * 4 + m) * 8192));
;             sb[m] = __builtin_nontemporal_load((const u32x4*)(gtb + koff + ((ai * 2 + bj) * 4 + m) * 8192));
;           }
.LBB0_562:
	s_or_b64 exec, exec, s[56:57]
	v_mov_b32_e32 v124, v248
	s_waitcnt vmcnt(0)
	s_barrier
	s_lshl_b64 s[48:49], s[48:49], 1
	v_ashrrev_i32_e32 v125, 31, v124
	v_lshrrev_b32_e32 v125, 26, v125
	v_lshlrev_b32_e32 v130, 4, v124
	v_add_u32_e32 v125, v124, v125
	v_bfe_i32 v124, v124, 27, 1
	v_lshrrev_b32_e32 v124, 22, v124
	v_add_u32_e32 v124, v130, v124
	v_and_b32_e32 v124, 0xfffffc00, v124
	v_sub_u32_e32 v124, v130, v124
	v_lshrrev_b32_e32 v126, 4, v124
	v_bitop3_b32 v124, v126, v124, 32 bitop3:0x6c
	v_ashrrev_i32_e32 v127, 31, v124
	v_ashrrev_i32_e32 v125, 6, v125
	v_lshrrev_b32_e32 v127, 26, v127
	v_lshlrev_b32_e32 v126, 3, v125
	v_add_u32_e32 v127, v124, v127
	v_and_b32_e32 v126, 0x1ffff0, v126
	v_lshrrev_b32_e32 v128, 6, v127
	v_lshlrev_b32_e32 v125, 5, v125
	v_and_b32_e32 v127, 0xc0, v127
	v_add_u32_e32 v126, v128, v126
	v_and_b32_e32 v125, 32, v125
	v_sub_u32_e32 v124, v124, v127
	v_ashrrev_i16_sdwa v124, v251, sext(v124) dst_sel:DWORD dst_unused:UNUSED_PAD src0_sel:DWORD src1_sel:BYTE_0
	v_lshl_or_b32 v125, v126, 11, v125
	v_add_u32_e32 v131, 0x2000, v130
	v_add_u32_sdwa v124, v125, sext(v124) dst_sel:DWORD dst_unused:UNUSED_PAD src0_sel:DWORD src1_sel:WORD_0
	v_ashrrev_i32_e32 v125, 31, v131
	v_lshrrev_b32_e32 v125, 22, v125
	v_add_u32_e32 v125, v131, v125
	v_ashrrev_i32_e32 v125, 10, v125
	v_mul_i32_i24_e32 v126, 0x400, v125
	v_sub_u32_e32 v126, v131, v126
	v_lshrrev_b32_e32 v127, 4, v126
	v_bitop3_b32 v126, v127, v126, 32 bitop3:0x6c
	v_ashrrev_i32_e32 v128, 31, v126
	v_lshrrev_b32_e32 v128, 26, v128
	v_lshlrev_b32_e32 v127, 3, v125
	v_add_u32_e32 v128, v126, v128
	v_and_b32_e32 v127, 0x1ffff0, v127
	v_lshrrev_b32_e32 v129, 6, v128
	v_lshlrev_b32_e32 v125, 5, v125
	v_and_b32_e32 v128, 0xc0, v128
	v_add_u32_e32 v127, v129, v127
	v_and_b32_e32 v125, 32, v125
	v_sub_u32_e32 v126, v126, v128
	v_ashrrev_i16_sdwa v126, v251, sext(v126) dst_sel:DWORD dst_unused:UNUSED_PAD src0_sel:DWORD src1_sel:BYTE_0
	v_lshl_or_b32 v125, v127, 11, v125
	v_add_u32_sdwa v126, v125, sext(v126) dst_sel:DWORD dst_unused:UNUSED_PAD src0_sel:DWORD src1_sel:WORD_0
	s_add_u32 s56, s68, s48
	v_ashrrev_i32_e32 v125, 31, v124
	v_add_u32_e32 v127, 0x10000, v130
	s_addc_u32 s57, s69, s49
	v_lshlrev_b64 v[124:125], 1, v[124:125]
	v_readfirstlane_b32 s48, v127
	v_ashrrev_i32_e32 v127, 31, v126
	v_add_u32_e32 v132, 0x12000, v130
	s_lshl_b32 s5, s5, 1
	v_lshl_add_u64 v[128:129], s[56:57], 0, v[124:125]
	s_mov_b32 m0, s48
	v_lshlrev_b64 v[126:127], 1, v[126:127]
	v_readfirstlane_b32 s48, v132
	s_add_u32 s58, s78, s5
	global_load_lds_dwordx4 v[128:129], off
	v_lshl_add_u64 v[128:129], s[56:57], 0, v[126:127]
	s_mov_b32 m0, s48
	s_addc_u32 s59, s79, 0
	v_readfirstlane_b32 s5, v130
	s_lshl_b64 s[48:49], s[60:61], 1
	global_load_lds_dwordx4 v[128:129], off
	v_lshl_add_u64 v[128:129], s[58:59], 0, v[124:125]
	s_mov_b32 m0, s5
	v_readfirstlane_b32 s5, v131
	s_add_u32 s60, s68, s48
	v_add_u32_e32 v131, 0x14000, v130
	global_load_lds_dwordx4 v[128:129], off
	v_lshl_add_u64 v[128:129], s[58:59], 0, v[126:127]
	s_mov_b32 m0, s5
	s_addc_u32 s61, s69, s49
	v_readfirstlane_b32 s5, v131
	v_add_u32_e32 v131, 0x16000, v130
	global_load_lds_dwordx4 v[128:129], off
	v_lshl_add_u64 v[128:129], s[60:61], 0, v[124:125]
	s_mov_b32 m0, s5
	v_readfirstlane_b32 s5, v131
	global_load_lds_dwordx4 v[128:129], off
	v_lshl_add_u64 v[128:129], s[60:61], 0, v[126:127]
	s_mov_b32 m0, s5
	s_lshl_b32 s5, s63, 1
	global_load_lds_dwordx4 v[128:129], off
	s_add_u32 s48, s78, s5
	v_add_u32_e32 v128, 0x4000, v130
	s_addc_u32 s49, s79, 0
	v_readfirstlane_b32 s5, v128
	v_lshl_add_u64 v[124:125], s[48:49], 0, v[124:125]
	s_mov_b32 m0, s5
	s_lshl_b32 s62, s62, 1
	global_load_lds_dwordx4 v[124:125], off
	v_lshl_add_u64 v[124:125], s[48:49], 0, v[126:127]
	v_add_u32_e32 v126, 0x6000, v130
	v_mov_b32_e32 v166, 0
	v_readfirstlane_b32 s5, v126
	s_mov_b32 m0, s5
	s_lshl_b32 s5, s2, 5
	s_add_i32 s62, s5, s62
	s_ashr_i32 s63, s62, 31
	s_lshl_b64 s[62:63], s[62:63], 17
	global_load_lds_dwordx4 v[124:125], off
	v_lshl_add_u64 v[132:133], v[244:245], 0, s[62:63]
	v_lshl_add_u64 v[246:247], v[132:133], 0, s[30:31]
	v_ashrrev_i32_e32 v167, 31, v166
	v_lshl_add_u64 v[124:125], v[132:133], 0, v[166:167]
	v_lshl_add_u64 v[128:129], v[246:247], 0, v[166:167]
	s_mov_b32 s101, 0
	global_load_dwordx4 v[204:207], v[132:133], off nt
	global_load_dwordx4 v[200:203], v[246:247], off nt
	s_mov_b32 s100, s64
	v_lshl_add_u64 v[228:229], v[132:133], 0, s[100:101]
	global_load_dwordx4 v[174:177], v[228:229], off nt
	s_mov_b32 s100, s64
	v_lshl_add_u64 v[228:229], v[246:247], 0, s[100:101]
	global_load_dwordx4 v[178:181], v[228:229], off nt
	s_mov_b32 s100, s87
	v_lshl_add_u64 v[228:229], v[132:133], 0, s[100:101]
	global_load_dwordx4 v[140:143], v[228:229], off nt
	s_mov_b32 s100, s87
	v_lshl_add_u64 v[228:229], v[246:247], 0, s[100:101]
	global_load_dwordx4 v[144:147], v[228:229], off nt
	s_mov_b32 s100, s88
	v_lshl_add_u64 v[228:229], v[132:133], 0, s[100:101]
	global_load_dwordx4 v[124:127], v[228:229], off nt
	s_mov_b32 s100, s88
	v_lshl_add_u64 v[228:229], v[246:247], 0, s[100:101]
	global_load_dwordx4 v[128:131], v[228:229], off nt
	s_mov_b32 s100, s67
	v_lshl_add_u64 v[228:229], v[132:133], 0, s[100:101]
	global_load_dwordx4 v[214:217], v[228:229], off nt
	s_mov_b32 s100, s67
	v_lshl_add_u64 v[228:229], v[246:247], 0, s[100:101]
	global_load_dwordx4 v[218:221], v[228:229], off nt
	s_mov_b32 s100, s72
	v_lshl_add_u64 v[228:229], v[132:133], 0, s[100:101]
	global_load_dwordx4 v[188:191], v[228:229], off nt
	s_mov_b32 s100, s72
	v_lshl_add_u64 v[228:229], v[246:247], 0, s[100:101]
	global_load_dwordx4 v[192:195], v[228:229], off nt
	s_mov_b32 s100, s81
	v_lshl_add_u64 v[228:229], v[132:133], 0, s[100:101]
	global_load_dwordx4 v[158:161], v[228:229], off nt
	s_mov_b32 s100, s81
	v_lshl_add_u64 v[228:229], v[246:247], 0, s[100:101]
	global_load_dwordx4 v[162:165], v[228:229], off nt
	s_nop 0
	s_nop 0
	s_waitcnt vmcnt(13)
; __device__ __forceinline__ float bflo(u32 v) { return __uint_as_float(v << 16); }
; __device__ __forceinline__ float bfhi(u32 v) { return __uint_as_float(v & 0xffff0000u); }
; __device__ void phase3(const Params& p) {
;     ...
;         for (int bj = 0; bj < 2; ++bj) {
;           asm volatile("" : "+v"(koff));
;           u32x4 sa[4], sb[4];
; #pragma unroll
;           for (int m = 0; m < 4; ++m) {
;             sa[m] = __builtin_nontemporal_load((const u32x4*)(gta + koff + ((ai * 2 + bj) * 4 + m) * 8192));
;             sb[m] = __builtin_nontemporal_load((const u32x4*)(gtb + koff + ((ai * 2 + bj) * 4 + m) * 8192));
;           }
; #pragma unroll
;           for (int m = 0; m < 4; ++m)
; #pragma unroll
;             for (int n = 0; n < 2; ++n) {
;               const u32x4 A4 = sa[m], B4 = sb[m];
;               acc[ai][bj][m][n][0] *= bflo(A4[2 * n]) / bflo(B4[2 * n]);
;               acc[ai][bj][m][n][1] *= bfhi(A4[2 * n]) / bfhi(B4[2 * n]);
;               acc[ai][bj][m][n][2] *= bflo(A4[2 * n + 1]) / bflo(B4[2 * n + 1]);
;               acc[ai][bj][m][n][3] *= bfhi(A4[2 * n + 1]) / bfhi(B4[2 * n + 1]);
;             }
;           asm volatile("" : "+v"(acc[ai][bj][0][0]), "+v"(acc[ai][bj][1][1]), "+v"(acc[ai][bj][2][0]), "+v"(acc[ai][bj][3][1]));
;         }
	v_and_b32_e32 v135, 0xffff0000, v204
	s_nop 0
	s_nop 0
	s_waitcnt vmcnt(12)
	v_and_b32_e32 v137, 0xffff0000, v200
	s_nop 0
	s_nop 0
	s_nop 0
	s_nop 0
	s_nop 0
	s_nop 0
	s_nop 0
	s_nop 0
	s_nop 0
	s_nop 0
	s_nop 0
	s_nop 0
	s_nop 0
	s_nop 0
	s_nop 0
	s_nop 0
	s_nop 0
	s_nop 0
	v_lshlrev_b32_e32 v134, 16, v204
	v_lshlrev_b32_e32 v136, 16, v200
	v_rcp_f32_e32 v138, v137
	s_nop 0
	v_mul_f32_e32 v135, v135, v138
	v_rcp_f32_e32 v137, v136
	s_nop 0
	v_mul_f32_e32 v134, v134, v137
	v_pk_mul_f32 v[0:1], v[0:1], v[134:135]
	v_and_b32_e32 v135, 0xffff0000, v205
	v_and_b32_e32 v137, 0xffff0000, v201
	v_lshlrev_b32_e32 v134, 16, v205
	v_lshlrev_b32_e32 v136, 16, v201
	v_rcp_f32_e32 v138, v137
	s_nop 0
	v_mul_f32_e32 v135, v135, v138
	v_rcp_f32_e32 v137, v136
	s_nop 0
	v_mul_f32_e32 v134, v134, v137
	v_pk_mul_f32 v[2:3], v[2:3], v[134:135]
	s_nop 0
	s_waitcnt vmcnt(11)
	v_and_b32_e32 v135, 0xffff0000, v176
	s_waitcnt vmcnt(10)
	v_and_b32_e32 v137, 0xffff0000, v180
	v_lshlrev_b32_e32 v134, 16, v176
	v_lshlrev_b32_e32 v136, 16, v180
	v_rcp_f32_e32 v138, v137
	s_nop 0
	v_mul_f32_e32 v135, v135, v138
	s_nop 0
	v_rcp_f32_e32 v137, v136
	s_nop 0
	v_mul_f32_e32 v134, v134, v137
	v_pk_mul_f32 v[4:5], v[4:5], v[134:135]
	v_and_b32_e32 v135, 0xffff0000, v177
	v_and_b32_e32 v137, 0xffff0000, v181
	v_lshlrev_b32_e32 v134, 16, v177
	v_lshlrev_b32_e32 v136, 16, v181
	v_rcp_f32_e32 v138, v137
	s_nop 0
	v_mul_f32_e32 v135, v135, v138
	s_nop 0
	v_rcp_f32_e32 v137, v136
	s_nop 0
	v_mul_f32_e32 v134, v134, v137
	v_pk_mul_f32 v[6:7], v[6:7], v[134:135]
	s_waitcnt vmcnt(9)
	v_and_b32_e32 v135, 0xffff0000, v140
	s_waitcnt vmcnt(8)
	v_and_b32_e32 v137, 0xffff0000, v144
	v_lshlrev_b32_e32 v134, 16, v140
	v_lshlrev_b32_e32 v136, 16, v144
	v_rcp_f32_e32 v138, v137
	s_nop 0
	v_mul_f32_e32 v135, v135, v138
	s_nop 0
	v_rcp_f32_e32 v137, v136
	s_nop 0
	v_mul_f32_e32 v134, v134, v137
	v_pk_mul_f32 v[8:9], v[8:9], v[134:135]
	v_and_b32_e32 v135, 0xffff0000, v141
	v_and_b32_e32 v137, 0xffff0000, v145
	v_lshlrev_b32_e32 v134, 16, v141
	v_lshlrev_b32_e32 v136, 16, v145
	v_rcp_f32_e32 v138, v137
	s_nop 0
	v_mul_f32_e32 v135, v135, v138
	s_nop 0
	v_rcp_f32_e32 v137, v136
	s_nop 0
	v_mul_f32_e32 v134, v134, v137
	v_pk_mul_f32 v[10:11], v[10:11], v[134:135]
	s_waitcnt vmcnt(7)
	v_lshlrev_b32_e32 v134, 16, v126
	v_and_b32_e32 v126, 0xffff0000, v126
	s_waitcnt vmcnt(6)
	v_lshlrev_b32_e32 v136, 16, v130
	v_and_b32_e32 v130, 0xffff0000, v130
	s_nop 0
	v_rcp_f32_e32 v135, v130
	s_nop 0
	v_mul_f32_e32 v135, v126, v135
	s_nop 0
	v_rcp_f32_e32 v126, v136
	s_nop 0
	v_mul_f32_e32 v134, v134, v126
	v_lshlrev_b32_e32 v126, 16, v127
	v_and_b32_e32 v127, 0xffff0000, v127
	v_lshlrev_b32_e32 v130, 16, v131
	v_and_b32_e32 v131, 0xffff0000, v131
	v_pk_mul_f32 v[12:13], v[12:13], v[134:135]
	s_nop 0
	v_rcp_f32_e32 v134, v131
	s_nop 0
	v_mul_f32_e32 v127, v127, v134
	s_nop 0
	v_rcp_f32_e32 v131, v130
	s_nop 0
	v_mul_f32_e32 v126, v126, v131
	v_pk_mul_f32 v[14:15], v[14:15], v[126:127]
	s_nop 0
	s_nop 0
	v_ashrrev_i32_e32 v167, 31, v166
	s_nop 0
	s_nop 0
	s_nop 0
	s_nop 0
	s_nop 0
	s_mov_b32 s100, s84
	v_lshl_add_u64 v[222:223], v[132:133], 0, s[100:101]
	global_load_dwordx4 v[134:137], v[222:223], off nt
	s_mov_b32 s100, s84
	v_lshl_add_u64 v[222:223], v[246:247], 0, s[100:101]
	global_load_dwordx4 v[138:141], v[222:223], off nt
	s_mov_b32 s100, s75
	v_lshl_add_u64 v[222:223], v[132:133], 0, s[100:101]
	global_load_dwordx4 v[228:231], v[222:223], off nt
	s_mov_b32 s100, s75
	v_lshl_add_u64 v[222:223], v[246:247], 0, s[100:101]
	global_load_dwordx4 v[232:235], v[222:223], off nt
	s_mov_b32 s100, s85
	v_lshl_add_u64 v[222:223], v[132:133], 0, s[100:101]
	global_load_dwordx4 v[208:211], v[222:223], off nt
	s_mov_b32 s100, s80
	v_lshl_add_u64 v[222:223], v[132:133], 0, s[100:101]
	global_load_dwordx4 v[180:183], v[222:223], off nt
	s_mov_b32 s100, s80
	v_lshl_add_u64 v[222:223], v[246:247], 0, s[100:101]
	global_load_dwordx4 v[184:187], v[222:223], off nt
	s_mov_b32 s100, s86
	v_lshl_add_u64 v[222:223], v[132:133], 0, s[100:101]
	global_load_dwordx4 v[152:155], v[222:223], off nt
	s_nop 0
	s_nop 1
	s_nop 0
	s_nop 0
	s_nop 1
	s_nop 0
	s_nop 0
	s_nop 1
	s_nop 0
	s_nop 0
	s_nop 1
	s_nop 0
	s_nop 0
	s_nop 1
	s_nop 0
	s_nop 0
	s_nop 0
	s_nop 0
	s_nop 0
	s_nop 0
	s_waitcnt vmcnt(12)
	v_lshlrev_b32_e32 v130, 16, v218
	s_nop 0
	v_and_b32_e32 v127, 0xffff0000, v214
	v_and_b32_e32 v131, 0xffff0000, v218
	v_lshlrev_b32_e32 v126, 16, v214
	v_rcp_f32_e32 v144, v131
	s_nop 0
	v_mul_f32_e32 v127, v127, v144
	s_nop 0
	v_rcp_f32_e32 v131, v130
	s_nop 0
	v_mul_f32_e32 v126, v126, v131
	v_pk_mul_f32 v[20:21], v[20:21], v[126:127]
	v_and_b32_e32 v127, 0xffff0000, v215
	v_and_b32_e32 v131, 0xffff0000, v219
	v_lshlrev_b32_e32 v126, 16, v215
	v_lshlrev_b32_e32 v130, 16, v219
	v_rcp_f32_e32 v144, v131
	s_nop 0
	v_mul_f32_e32 v127, v127, v144
	s_nop 0
	v_rcp_f32_e32 v131, v130
	s_nop 0
	v_mul_f32_e32 v126, v126, v131
	v_pk_mul_f32 v[22:23], v[22:23], v[126:127]
	s_waitcnt vmcnt(11)
	v_and_b32_e32 v127, 0xffff0000, v190
	s_waitcnt vmcnt(10)
	v_and_b32_e32 v131, 0xffff0000, v194
	v_lshlrev_b32_e32 v126, 16, v190
	v_lshlrev_b32_e32 v130, 16, v194
	v_rcp_f32_e32 v144, v131
	s_nop 0
	v_mul_f32_e32 v127, v127, v144
	s_nop 0
	v_rcp_f32_e32 v131, v130
	s_nop 0
	v_mul_f32_e32 v126, v126, v131
	v_pk_mul_f32 v[28:29], v[28:29], v[126:127]
	v_and_b32_e32 v127, 0xffff0000, v191
	v_and_b32_e32 v131, 0xffff0000, v195
	v_lshlrev_b32_e32 v126, 16, v191
	v_lshlrev_b32_e32 v130, 16, v195
	v_rcp_f32_e32 v144, v131
	s_nop 0
	v_mul_f32_e32 v127, v127, v144
	s_nop 0
	v_rcp_f32_e32 v131, v130
	s_nop 0
	v_mul_f32_e32 v126, v126, v131
	v_pk_mul_f32 v[30:31], v[30:31], v[126:127]
	s_waitcnt vmcnt(9)
; __device__ __forceinline__ float bflo(u32 v) { return __uint_as_float(v << 16); }
; __device__ __forceinline__ float bfhi(u32 v) { return __uint_as_float(v & 0xffff0000u); }
; __device__ void phase3(const Params& p) {
;     ...
;         for (int bj = 0; bj < 2; ++bj) {
;           asm volatile("" : "+v"(koff));
;           u32x4 sa[4], sb[4];
; #pragma unroll
;           for (int m = 0; m < 4; ++m) {
;             sa[m] = __builtin_nontemporal_load((const u32x4*)(gta + koff + ((ai * 2 + bj) * 4 + m) * 8192));
;             sb[m] = __builtin_nontemporal_load((const u32x4*)(gtb + koff + ((ai * 2 + bj) * 4 + m) * 8192));
;           }
; #pragma unroll
;           for (int m = 0; m < 4; ++m)
; #pragma unroll
;             for (int n = 0; n < 2; ++n) {
;               const u32x4 A4 = sa[m], B4 = sb[m];
;               acc[ai][bj][m][n][0] *= bflo(A4[2 * n]) / bflo(B4[2 * n]);
;               acc[ai][bj][m][n][1] *= bfhi(A4[2 * n]) / bfhi(B4[2 * n]);
;               acc[ai][bj][m][n][2] *= bflo(A4[2 * n + 1]) / bflo(B4[2 * n + 1]);
;               acc[ai][bj][m][n][3] *= bfhi(A4[2 * n + 1]) / bfhi(B4[2 * n + 1]);
;             }
;           asm volatile("" : "+v"(acc[ai][bj][0][0]), "+v"(acc[ai][bj][1][1]), "+v"(acc[ai][bj][2][0]), "+v"(acc[ai][bj][3][1]));
;         }
	v_and_b32_e32 v127, 0xffff0000, v158
	s_waitcnt vmcnt(8)
	v_and_b32_e32 v131, 0xffff0000, v162
	v_lshlrev_b32_e32 v126, 16, v158
	v_lshlrev_b32_e32 v130, 16, v162
	v_rcp_f32_e32 v144, v131
	s_nop 0
	v_mul_f32_e32 v127, v127, v144
	s_nop 0
	v_rcp_f32_e32 v131, v130
	s_nop 0
	v_mul_f32_e32 v126, v126, v131
	v_pk_mul_f32 v[36:37], v[36:37], v[126:127]
	v_and_b32_e32 v127, 0xffff0000, v159
	v_and_b32_e32 v131, 0xffff0000, v163
	v_lshlrev_b32_e32 v126, 16, v159
	v_lshlrev_b32_e32 v130, 16, v163
	v_rcp_f32_e32 v144, v131
	s_nop 0
	v_mul_f32_e32 v127, v127, v144
	s_nop 0
	v_rcp_f32_e32 v131, v130
	s_nop 0
	v_mul_f32_e32 v126, v126, v131
	v_pk_mul_f32 v[38:39], v[38:39], v[126:127]
	s_waitcnt vmcnt(7)
	v_and_b32_e32 v127, 0xffff0000, v136
	s_nop 0
	s_waitcnt vmcnt(6)
	v_and_b32_e32 v131, 0xffff0000, v140
	v_lshlrev_b32_e32 v126, 16, v136
	v_lshlrev_b32_e32 v130, 16, v140
	s_nop 0
	v_rcp_f32_e32 v136, v131
	s_nop 0
	v_mul_f32_e32 v127, v127, v136
	s_nop 0
	v_rcp_f32_e32 v131, v130
	s_nop 0
	v_mul_f32_e32 v126, v126, v131
	v_pk_mul_f32 v[44:45], v[44:45], v[126:127]
	v_and_b32_e32 v127, 0xffff0000, v137
	v_and_b32_e32 v131, 0xffff0000, v141
	v_lshlrev_b32_e32 v126, 16, v137
	v_lshlrev_b32_e32 v130, 16, v141
	v_rcp_f32_e32 v136, v131
	s_nop 0
	v_mul_f32_e32 v127, v127, v136
	s_nop 0
	v_rcp_f32_e32 v131, v130
	s_nop 0
	v_mul_f32_e32 v126, v126, v131
	v_pk_mul_f32 v[46:47], v[46:47], v[126:127]
	s_nop 0
	s_nop 0
	v_ashrrev_i32_e32 v167, 31, v166
	s_nop 0
	s_nop 0
	s_nop 0
	s_nop 0
	s_nop 0
	s_mov_b32 s100, s85
	v_lshl_add_u64 v[168:169], v[246:247], 0, s[100:101]
	global_load_dwordx4 v[212:215], v[168:169], off nt
	s_mov_b32 s100, s86
	v_lshl_add_u64 v[168:169], v[246:247], 0, s[100:101]
	global_load_dwordx4 v[156:159], v[168:169], off nt
	s_mov_b32 s100, s65
	v_lshl_add_u64 v[168:169], v[132:133], 0, s[100:101]
	global_load_dwordx4 v[236:239], v[168:169], off nt
	s_mov_b32 s100, s65
	v_lshl_add_u64 v[168:169], v[246:247], 0, s[100:101]
	global_load_dwordx4 v[240:243], v[168:169], off nt
	s_mov_b32 s100, s66
	v_lshl_add_u64 v[168:169], v[132:133], 0, s[100:101]
	global_load_dwordx4 v[222:225], v[168:169], off nt
	s_mov_b32 s100, s73
	v_lshl_add_u64 v[168:169], v[132:133], 0, s[100:101]
	global_load_dwordx4 v[194:197], v[168:169], off nt
	s_mov_b32 s100, s73
	v_lshl_add_u64 v[168:169], v[246:247], 0, s[100:101]
	global_load_dwordx4 v[198:201], v[168:169], off nt
	s_mov_b32 s100, s74
	v_lshl_add_u64 v[168:169], v[246:247], 0, s[100:101]
	global_load_dwordx4 v[170:173], v[168:169], off nt
	s_nop 0
	s_nop 1
	s_nop 0
	s_nop 0
	s_nop 1
	s_nop 0
	s_nop 0
	s_nop 1
	s_nop 0
	s_nop 0
	s_nop 1
	s_nop 0
	s_nop 0
	s_nop 1
	s_nop 0
	s_nop 0
	s_nop 0
	s_nop 0
	s_nop 0
	s_nop 0
	s_waitcnt vmcnt(12)
	v_lshlrev_b32_e32 v130, 16, v232
	s_nop 0
	v_and_b32_e32 v127, 0xffff0000, v228
	v_and_b32_e32 v131, 0xffff0000, v232
	v_lshlrev_b32_e32 v126, 16, v228
	v_rcp_f32_e32 v136, v131
	s_nop 0
	v_mul_f32_e32 v127, v127, v136
	s_nop 0
	v_rcp_f32_e32 v131, v130
	s_nop 0
	v_mul_f32_e32 v126, v126, v131
	v_pk_mul_f32 v[52:53], v[52:53], v[126:127]
	v_and_b32_e32 v127, 0xffff0000, v229
	v_and_b32_e32 v131, 0xffff0000, v233
	v_lshlrev_b32_e32 v126, 16, v229
	v_lshlrev_b32_e32 v130, 16, v233
	v_rcp_f32_e32 v136, v131
	s_nop 0
	v_mul_f32_e32 v127, v127, v136
	s_nop 0
	v_rcp_f32_e32 v131, v130
	s_nop 0
	v_mul_f32_e32 v126, v126, v131
	v_pk_mul_f32 v[54:55], v[54:55], v[126:127]
	s_waitcnt vmcnt(11)
	v_and_b32_e32 v127, 0xffff0000, v210
	s_waitcnt vmcnt(7)
	v_and_b32_e32 v131, 0xffff0000, v214
	v_lshlrev_b32_e32 v126, 16, v210
	v_lshlrev_b32_e32 v130, 16, v214
	v_rcp_f32_e32 v136, v131
	s_nop 0
	v_mul_f32_e32 v127, v127, v136
	s_nop 0
	v_rcp_f32_e32 v131, v130
	s_nop 0
	v_mul_f32_e32 v126, v126, v131
	v_pk_mul_f32 v[60:61], v[60:61], v[126:127]
	v_and_b32_e32 v127, 0xffff0000, v211
	v_and_b32_e32 v131, 0xffff0000, v215
	v_lshlrev_b32_e32 v126, 16, v211
	v_lshlrev_b32_e32 v130, 16, v215
	v_rcp_f32_e32 v136, v131
	s_nop 0
	v_mul_f32_e32 v127, v127, v136
	s_nop 0
	v_rcp_f32_e32 v131, v130
	s_nop 0
	v_mul_f32_e32 v126, v126, v131
	v_pk_mul_f32 v[62:63], v[62:63], v[126:127]
	v_and_b32_e32 v127, 0xffff0000, v180
	v_and_b32_e32 v131, 0xffff0000, v184
	v_lshlrev_b32_e32 v126, 16, v180
	v_lshlrev_b32_e32 v130, 16, v184
	v_rcp_f32_e32 v136, v131
	s_nop 0
	v_mul_f32_e32 v127, v127, v136
	s_nop 0
	v_rcp_f32_e32 v131, v130
	s_nop 0
	v_mul_f32_e32 v126, v126, v131
	v_pk_mul_f32 v[68:69], v[68:69], v[126:127]
	v_and_b32_e32 v127, 0xffff0000, v181
	v_and_b32_e32 v131, 0xffff0000, v185
	v_lshlrev_b32_e32 v126, 16, v181
	v_lshlrev_b32_e32 v130, 16, v185
	v_rcp_f32_e32 v136, v131
	s_nop 0
	v_mul_f32_e32 v127, v127, v136
	s_nop 0
	v_rcp_f32_e32 v131, v130
	s_nop 0
	v_mul_f32_e32 v126, v126, v131
	v_pk_mul_f32 v[70:71], v[70:71], v[126:127]
	v_and_b32_e32 v127, 0xffff0000, v154
	s_nop 0
	s_waitcnt vmcnt(6)
; __device__ __forceinline__ float bflo(u32 v) { return __uint_as_float(v << 16); }
; __device__ __forceinline__ float bfhi(u32 v) { return __uint_as_float(v & 0xffff0000u); }
; #define BAR __builtin_amdgcn_s_barrier()
; __device__ __forceinline__ void gemm_main(const u16* __restrict__ A, const u16* __restrict__ Bt, const int K, const int Klen,
;                                           const int brow, const int bcol, f32x4 (&acc)[2][2][4][2]) {
;     ...
;   if (wr == 1) BAR;
; __device__ void phase3(const Params& p) {
;     ...
;         for (int bj = 0; bj < 2; ++bj) {
;           asm volatile("" : "+v"(koff));
;           u32x4 sa[4], sb[4];
; #pragma unroll
;           for (int m = 0; m < 4; ++m) {
;             sa[m] = __builtin_nontemporal_load((const u32x4*)(gta + koff + ((ai * 2 + bj) * 4 + m) * 8192));
;             sb[m] = __builtin_nontemporal_load((const u32x4*)(gtb + koff + ((ai * 2 + bj) * 4 + m) * 8192));
;           }
; #pragma unroll
;           for (int m = 0; m < 4; ++m)
; #pragma unroll
;             for (int n = 0; n < 2; ++n) {
;               const u32x4 A4 = sa[m], B4 = sb[m];
;               acc[ai][bj][m][n][0] *= bflo(A4[2 * n]) / bflo(B4[2 * n]);
;               acc[ai][bj][m][n][1] *= bfhi(A4[2 * n]) / bfhi(B4[2 * n]);
;               acc[ai][bj][m][n][2] *= bflo(A4[2 * n + 1]) / bflo(B4[2 * n + 1]);
;               acc[ai][bj][m][n][3] *= bfhi(A4[2 * n + 1]) / bfhi(B4[2 * n + 1]);
;             }
;           asm volatile("" : "+v"(acc[ai][bj][0][0]), "+v"(acc[ai][bj][1][1]), "+v"(acc[ai][bj][2][0]), "+v"(acc[ai][bj][3][1]));
;         }
	v_and_b32_e32 v131, 0xffff0000, v158
	v_lshlrev_b32_e32 v126, 16, v154
	v_lshlrev_b32_e32 v130, 16, v158
	v_rcp_f32_e32 v136, v131
	s_nop 0
	v_mul_f32_e32 v127, v127, v136
	s_nop 0
	v_rcp_f32_e32 v131, v130
	s_nop 0
	v_mul_f32_e32 v126, v126, v131
	v_pk_mul_f32 v[76:77], v[76:77], v[126:127]
	v_and_b32_e32 v127, 0xffff0000, v155
	v_and_b32_e32 v131, 0xffff0000, v159
	v_lshlrev_b32_e32 v126, 16, v155
	v_lshlrev_b32_e32 v130, 16, v159
	v_rcp_f32_e32 v136, v131
	s_nop 0
	v_mul_f32_e32 v127, v127, v136
	s_nop 0
	v_rcp_f32_e32 v131, v130
	s_nop 0
	v_mul_f32_e32 v126, v126, v131
	v_pk_mul_f32 v[78:79], v[78:79], v[126:127]
	s_nop 0
	s_nop 0
	v_ashrrev_i32_e32 v167, 31, v166
	s_nop 0
	s_nop 0
	s_nop 0
	s_nop 0
	s_nop 0
	s_mov_b32 s100, s66
	v_lshl_add_u64 v[168:169], v[246:247], 0, s[100:101]
	global_load_dwordx4 v[226:229], v[168:169], off nt
	s_mov_b32 s100, s74
	v_lshl_add_u64 v[168:169], v[132:133], 0, s[100:101]
	global_load_dwordx4 v[166:169], v[168:169], off nt
	s_nop 0
	s_nop 1
	s_nop 0
	s_nop 0
	s_nop 1
	s_nop 0
	s_nop 0
	s_nop 1
	s_nop 0
	s_nop 0
	s_nop 1
	s_nop 0
	s_nop 0
	s_nop 1
	s_nop 0
	s_nop 0
	s_nop 0
	s_nop 0
	s_nop 0
	s_nop 0
	s_waitcnt vmcnt(6)
	v_lshlrev_b32_e32 v130, 16, v240
	s_nop 0
	v_and_b32_e32 v127, 0xffff0000, v236
	v_and_b32_e32 v131, 0xffff0000, v240
	v_lshlrev_b32_e32 v126, 16, v236
	v_rcp_f32_e32 v132, v131
	s_nop 0
	v_mul_f32_e32 v127, v127, v132
	s_nop 0
	v_rcp_f32_e32 v131, v130
	s_nop 0
	v_mul_f32_e32 v126, v126, v131
	v_pk_mul_f32 v[88:89], v[88:89], v[126:127]
	v_and_b32_e32 v127, 0xffff0000, v237
	v_and_b32_e32 v131, 0xffff0000, v241
	v_lshlrev_b32_e32 v126, 16, v237
	v_lshlrev_b32_e32 v130, 16, v241
	v_rcp_f32_e32 v132, v131
	s_nop 0
	v_mul_f32_e32 v127, v127, v132
	s_nop 0
	v_rcp_f32_e32 v131, v130
	s_nop 0
	v_mul_f32_e32 v126, v126, v131
	v_pk_mul_f32 v[90:91], v[90:91], v[126:127]
	s_waitcnt vmcnt(5)
	v_and_b32_e32 v127, 0xffff0000, v224
	s_waitcnt vmcnt(1)
	v_and_b32_e32 v131, 0xffff0000, v228
	v_lshlrev_b32_e32 v126, 16, v224
	v_lshlrev_b32_e32 v130, 16, v228
	v_rcp_f32_e32 v132, v131
	s_nop 0
	v_mul_f32_e32 v127, v127, v132
	s_nop 0
	v_rcp_f32_e32 v131, v130
	s_nop 0
	v_mul_f32_e32 v126, v126, v131
	v_pk_mul_f32 v[96:97], v[96:97], v[126:127]
	v_and_b32_e32 v127, 0xffff0000, v225
	v_and_b32_e32 v131, 0xffff0000, v229
	v_lshlrev_b32_e32 v126, 16, v225
	v_lshlrev_b32_e32 v130, 16, v229
	v_rcp_f32_e32 v132, v131
	s_nop 0
	v_mul_f32_e32 v127, v127, v132
	s_nop 0
	v_rcp_f32_e32 v131, v130
	s_nop 0
	v_mul_f32_e32 v126, v126, v131
	v_pk_mul_f32 v[98:99], v[98:99], v[126:127]
	v_and_b32_e32 v127, 0xffff0000, v194
	v_and_b32_e32 v131, 0xffff0000, v198
	v_lshlrev_b32_e32 v126, 16, v194
	v_lshlrev_b32_e32 v130, 16, v198
	v_rcp_f32_e32 v132, v131
	s_nop 0
	v_mul_f32_e32 v127, v127, v132
	s_nop 0
	v_rcp_f32_e32 v131, v130
	s_nop 0
	v_mul_f32_e32 v126, v126, v131
	v_pk_mul_f32 v[104:105], v[104:105], v[126:127]
	v_and_b32_e32 v127, 0xffff0000, v195
	v_and_b32_e32 v131, 0xffff0000, v199
	v_lshlrev_b32_e32 v126, 16, v195
	v_lshlrev_b32_e32 v130, 16, v199
	v_rcp_f32_e32 v132, v131
	s_nop 0
	v_mul_f32_e32 v127, v127, v132
	s_nop 0
	v_rcp_f32_e32 v131, v130
	s_nop 0
	v_mul_f32_e32 v126, v126, v131
	v_pk_mul_f32 v[106:107], v[106:107], v[126:127]
	s_waitcnt vmcnt(0)
	v_and_b32_e32 v127, 0xffff0000, v168
	s_nop 0
	v_and_b32_e32 v131, 0xffff0000, v172
	v_lshlrev_b32_e32 v126, 16, v168
	v_lshlrev_b32_e32 v130, 16, v172
	v_rcp_f32_e32 v132, v131
	s_nop 0
	v_mul_f32_e32 v127, v127, v132
	s_nop 0
	v_rcp_f32_e32 v131, v130
	s_nop 0
	v_mul_f32_e32 v126, v126, v131
	v_pk_mul_f32 v[112:113], v[112:113], v[126:127]
	v_and_b32_e32 v127, 0xffff0000, v169
	v_and_b32_e32 v131, 0xffff0000, v173
	v_lshlrev_b32_e32 v126, 16, v169
	v_lshlrev_b32_e32 v130, 16, v173
	v_rcp_f32_e32 v132, v131
	s_nop 0
	v_mul_f32_e32 v127, v127, v132
	v_mov_b32_e32 v140, v248
	v_rcp_f32_e32 v131, v130
	s_nop 0
	v_mul_f32_e32 v126, v126, v131
	v_pk_mul_f32 v[114:115], v[114:115], v[126:127]
	s_nop 0
	s_nop 0
	v_ashrrev_i32_e32 v136, 8, v140
	v_cmp_eq_u32_e32 vcc, 1, v136
	s_and_saveexec_b64 s[62:63], vcc
	s_cbranch_execz .LBB0_564
	s_barrier
